# speedup vs baseline: 1.0015x; 1.0015x over previous
; __device__ __forceinline__ uint32_t tilemask(int d) {
;   if (d < 0) return 0u;
;   if (d >= 51) return 0xffffu;
;   const int q = d >> 4, r = min(d & 15, 3);
;   return ((1u << (4 * q)) - 1u) | (((2u << r) - 1u) << (4 * q));
; }
; __device__ __forceinline__ void attn_phase(const Params& p, int o, char* smem) {
;     ...
; #pragma unroll
;         for (int qt = 0; qt < 2; ++qt)
;           vm[qt] = ((selm[qt] >> jb) & 1ull) ? tilemask(pos[qt] - 64 * jb - 4 * fq) : 0u;
.LBB0_639:
	s_or_b64 exec, exec, s[6:7]
	v_readfirstlane_b32 s8, v134
	v_lshlrev_b64 v[92:93], v134, 1
	v_lshlrev_b32_e32 v94, 6, v134
	s_cmp_eq_u32 s8, s62
	s_cbranch_scc1 .Lslc_mask_slow
	v_and_b32_e32 v97, v93, v57
	v_and_b32_e32 v96, v92, v56
	v_mov_b32_e32 v142, 0xffff
	v_cmp_ne_u64_e32 vcc, 0, v[96:97]
	v_and_b32_e32 v93, v93, v59
	v_and_b32_e32 v92, v92, v58
	v_cndmask_b32_e32 v142, 0, v142, vcc
	v_mov_b32_e32 v140, 0xffff
	v_cmp_ne_u64_e32 vcc, 0, v[92:93]
	s_nop 0
	v_cndmask_b32_e32 v140, 0, v140, vcc
	s_branch .Lslc_mask_done
.Lslc_mask_slow:
	v_and_b32_e32 v97, v93, v57
	v_and_b32_e32 v96, v92, v56
	v_sub_u32_e32 v94, v125, v94
	v_cmp_ne_u64_e32 vcc, 0, v[96:97]
	v_mov_b32_e32 v140, 0
	v_mov_b32_e32 v142, 0
	s_and_saveexec_b64 s[6:7], vcc
	s_cbranch_execz .LBB0_645
	v_add_u32_e32 v95, v94, v228
	v_cmp_lt_i32_e32 vcc, -1, v95
	v_mov_b32_e32 v142, 0
	s_and_saveexec_b64 s[8:9], vcc
	s_cbranch_execz .LBB0_644
	v_cmp_gt_u32_e32 vcc, 51, v95
	v_mov_b32_e32 v142, 0xffff
	s_and_saveexec_b64 s[10:11], vcc
	v_and_b32_e32 v96, 15, v95
	v_min_u32_e32 v96, 3, v96
	v_lshrrev_b32_e32 v95, 2, v95
	v_and_b32_e32 v95, 12, v95
	v_lshlrev_b32_e64 v96, v96, 2
	v_lshlrev_b32_e64 v97, v95, -1
	v_add_lshl_u32 v95, v96, -1, v95
	v_bitop3_b32 v142, v95, v97, v95 bitop3:0xf3
	s_or_b64 exec, exec, s[10:11]

; template <bool BOUNDARY, bool Q0, bool Q1>
; __device__ __forceinline__ void attn_tile(const bf16* Ks, const bf16* Vt, const bf16x8 (&Qf)[2][2], const uint32_t (&vm)[2],
;                                           float (&m)[2], float (&l)[2], f32x4 (&O)[4][2], int fr, int fq) {
;   f32x4 S[4][2];
; #pragma unroll
;   for (int kt = 0; kt < 4; ++kt) {
;     S[kt][0] = f32x4{0.f, 0.f, 0.f, 0.f};
;     S[kt][1] = f32x4{0.f, 0.f, 0.f, 0.f};
; #pragma unroll
;     for (int ks = 0; ks < 2; ++ks) {
;       const bf16x8 kf = *(const bf16x8*)(Ks + (16 * kt + fr) * KS_LD + 32 * ks + 8 * fq);
;       if (Q0) S[kt][0] = __builtin_amdgcn_mfma_f32_16x16x32_bf16(kf, Qf[0][ks], S[kt][0], 0, 0, 0);
;       if (Q1) S[kt][1] = __builtin_amdgcn_mfma_f32_16x16x32_bf16(kf, Qf[1][ks], S[kt][1], 0, 0, 0);
;     }
;   }
; #pragma unroll
;   for (int qt = 0; qt < 2; ++qt) {
;     if ((qt == 0 && !Q0) || (qt == 1 && !Q1)) continue;
;     float mx, mxu;
;     if (BOUNDARY) {
;       mx = m[qt];
; #pragma unroll
;       for (int kt = 0; kt < 4; ++kt)
; #pragma unroll
;         for (int j = 0; j < 4; ++j) {
;           const float s2 = S[kt][qt][j];
;           if ((vm[qt] >> (kt * 4 + j)) & 1u) mx = fmaxf(mx, s2);
;         }
;       mx = fmaxf(mx, __shfl_xor(mx, 16));
;       mx = fmaxf(mx, __shfl_xor(mx, 32));
;       mxu = mx;
;     } else {
;       float rm = -3.0e38f;
; #pragma unroll
;       for (int kt = 0; kt < 4; ++kt)
; #pragma unroll
;         for (int j = 0; j < 4; ++j) {
;           rm = fmaxf(rm, S[kt][qt][j]);
;         }
;       rm = fmaxf(rm, __shfl_xor(rm, 16));
;       rm = fmaxf(rm, __shfl_xor(rm, 32));
;       const bool rv = vm[qt] != 0u;
;       mx = rv ? fmaxf(m[qt], rm) : m[qt];
;       mxu = rv ? mx : 3.0e38f;
;     }
;     const float alpha = __builtin_amdgcn_exp2f(m[qt] - mx);
;     m[qt] = mx;
;     float ls = 0.f;
; #pragma unroll
;     for (int kt = 0; kt < 4; ++kt)
; #pragma unroll
;       for (int j = 0; j < 4; ++j) {
;         float pv;
;         if (BOUNDARY) pv = ((vm[qt] >> (kt * 4 + j)) & 1u) ? __builtin_amdgcn_exp2f(S[kt][qt][j] - mxu) : 0.f;
;         else pv = __builtin_amdgcn_exp2f(S[kt][qt][j] - mxu);
;         S[kt][qt][j] = pv;
;         ls += pv;
;       }
;     l[qt] = l[qt] * alpha + ls;
; #pragma unroll
;     for (int dt = 0; dt < 4; ++dt) {
.Lslc_mask_done:
	v_cmp_ne_u32_e64 s[6:7], 0, v142
	v_mul_lo_u32 v138, v135, s40
	v_cmp_ne_u32_e32 vcc, s62, v134
	v_cndmask_b32_e64 v146, 0, 1, s[6:7]
	v_cmp_ne_u32_e64 s[6:7], 0, v140
	s_nop 1
	v_cndmask_b32_e64 v145, 0, 1, s[6:7]
	s_and_saveexec_b64 s[6:7], vcc
	s_xor_b64 s[6:7], exec, s[6:7]
	s_cbranch_execz .LBB0_656
	v_cmp_ne_u32_e64 s[8:9], 0, v142
	v_cmp_ne_u32_e64 s[10:11], 0, v140
	s_cmp_eq_u64 s[8:9], 0
	s_cselect_b64 s[12:13], -1, 0
	s_cmp_lg_u64 s[8:9], 0
	s_cselect_b64 s[8:9], -1, 0
	s_cmp_lg_u64 s[10:11], 0
	s_cselect_b64 s[10:11], -1, 0
	s_and_b64 s[8:9], s[8:9], s[10:11]
	s_andn2_b64 vcc, exec, s[8:9]
	s_mov_b64 s[8:9], -1
	s_cbranch_vccz .LBB0_665
	s_and_b64 vcc, exec, s[12:13]
	s_cbranch_vccz .LBB0_662
	s_andn2_b64 vcc, exec, s[10:11]
	s_cbranch_vccnz .LBB0_661
	v_add_u32_e32 v100, v138, v152
	v_add_u32_e32 v96, v100, v230
	ds_read_b128 v[92:95], v96
	v_add_u32_e32 v108, v100, v163
	ds_read_b128 v[100:103], v108 offset:64
	ds_read_b128 v[96:99], v96 offset:64
	ds_read_b128 v[104:107], v108 offset:2368
	v_cmp_eq_u32_e32 vcc, 0, v140
	s_mov_b64 s[8:9], 0
	s_waitcnt lgkmcnt(3)
	v_mfma_f32_16x16x32_bf16 v[92:95], v[92:95], v[8:11], 0
	s_waitcnt lgkmcnt(1)
	v_mfma_f32_16x16x32_bf16 v[92:95], v[96:99], v[12:15], v[92:95]
	ds_read_b128 v[96:99], v108
	s_waitcnt lgkmcnt(0)
	v_mfma_f32_16x16x32_bf16 v[96:99], v[96:99], v[8:11], 0
	v_mfma_f32_16x16x32_bf16 v[96:99], v[100:103], v[12:15], v[96:99]
	ds_read_b128 v[100:103], v108 offset:2304
	s_waitcnt lgkmcnt(0)
	v_mfma_f32_16x16x32_bf16 v[100:103], v[100:103], v[8:11], 0
	v_mfma_f32_16x16x32_bf16 v[100:103], v[104:107], v[12:15], v[100:103]
	ds_read_b128 v[104:107], v108 offset:4608
	ds_read_b128 v[108:111], v108 offset:4672
	s_waitcnt lgkmcnt(1)
	v_mfma_f32_16x16x32_bf16 v[104:107], v[104:107], v[8:11], 0
	s_waitcnt lgkmcnt(0)
	v_mfma_f32_16x16x32_bf16 v[104:107], v[108:111], v[12:15], v[104:107]
	v_max3_f32 v108, v92, s49, v93
	v_max3_f32 v108, v108, v94, v95
	v_max3_f32 v108, v108, v96, v97
	v_max3_f32 v108, v108, v98, v99
	v_max3_f32 v108, v108, v100, v101
	v_max3_f32 v108, v108, v102, v103
	s_nop 1
	v_max3_f32 v108, v108, v104, v105
	v_max3_f32 v108, v108, v106, v107
	ds_bpermute_b32 v109, v225, v108
	s_waitcnt lgkmcnt(0)
	v_max_f32_e32 v109, v109, v109
	v_max_f32_e32 v108, v108, v109
	ds_bpermute_b32 v109, v224, v108
	s_waitcnt lgkmcnt(0)
	v_max3_f32 v108, v139, v108, v109
	v_cndmask_b32_e32 v109, v108, v215, vcc
	v_sub_f32_e32 v93, v93, v109
	v_exp_f32_e32 v111, v93
	v_sub_f32_e32 v93, v94, v109
	v_sub_f32_e32 v92, v92, v109
	v_exp_f32_e32 v112, v93
	v_sub_f32_e32 v93, v95, v109
	v_exp_f32_e32 v110, v92
	v_exp_f32_e32 v113, v93
	v_sub_f32_e32 v93, v96, v109
	v_exp_f32_e32 v114, v93
	v_sub_f32_e32 v93, v97, v109
	v_exp_f32_e32 v115, v93
	v_sub_f32_e32 v93, v98, v109
	v_exp_f32_e32 v116, v93
	v_sub_f32_e32 v93, v99, v109
	v_add_f32_e32 v92, 0, v110
	v_exp_f32_e32 v117, v93
	v_sub_f32_e32 v93, v100, v109
	v_add_f32_e32 v92, v111, v92
	v_exp_f32_e32 v118, v93
	v_sub_f32_e32 v93, v101, v109
	v_add_f32_e32 v92, v112, v92
	v_exp_f32_e32 v119, v93
	v_sub_f32_e32 v93, v102, v109
	v_add_f32_e32 v92, v113, v92
	v_exp_f32_e32 v120, v93
	v_sub_f32_e32 v93, v103, v109
	v_cndmask_b32_e32 v144, v108, v139, vcc
	v_add_f32_e32 v92, v114, v92
	v_exp_f32_e32 v121, v93
	v_sub_f32_e32 v93, v104, v109
	v_sub_f32_e32 v108, v139, v144
	v_add_f32_e32 v92, v115, v92
	v_exp_f32_e32 v122, v93
	v_sub_f32_e32 v93, v105, v109
	v_add_f32_e32 v92, v116, v92
	v_exp_f32_e32 v123, v93
	v_sub_f32_e32 v93, v106, v109
	v_exp_f32_e32 v104, v108
	v_cvt_pk_bf16_f32 v108, v110, v111
	v_cvt_pk_bf16_f32 v111, v116, v117
	v_lshlrev_b32_e32 v116, 1, v223
	v_exp_f32_e32 v143, v93
	v_sub_f32_e32 v93, v107, v109
	v_cvt_pk_bf16_f32 v109, v112, v113
	v_add3_u32 v112, v138, v231, v116
	v_add_f32_e32 v92, v117, v92
	v_add_u32_e32 v117, 0x2000, v112
	v_cvt_pk_bf16_f32 v110, v114, v115
	ds_read2_b64 v[112:115], v117 offset0:128 offset1:132
	v_add_f32_e32 v92, v118, v92
	v_add_f32_e32 v92, v119, v92
	v_add_f32_e32 v92, v120, v92
	v_add_f32_e32 v92, v121, v92
	v_exp_f32_e32 v145, v93
	v_add_f32_e32 v92, v122, v92
	v_add_f32_e32 v92, v123, v92
	v_add_f32_e32 v92, v143, v92
	v_add_f32_e32 v146, v145, v92
	v_pk_mul_f32 v[94:95], v[74:75], v[104:105] op_sel_hi:[1,0]
	v_pk_mul_f32 v[92:93], v[72:73], v[104:105] op_sel_hi:[1,0]
	v_pk_mul_f32 v[98:99], v[70:71], v[104:105] op_sel_hi:[1,0]
	v_pk_mul_f32 v[96:97], v[68:69], v[104:105] op_sel_hi:[1,0]
	s_waitcnt lgkmcnt(0)
	v_mfma_f32_16x16x32_bf16 v[92:95], v[112:115], v[108:111], v[92:95]
	v_lshlrev_b32_e32 v112, 1, v233
	v_add3_u32 v116, v138, v112, v116
	v_add_u32_e32 v147, 0x2000, v116
	ds_read2_b64 v[112:115], v147 offset0:128 offset1:132
	v_add_u32_e32 v148, 0x2800, v116
	s_waitcnt lgkmcnt(0)
	v_mfma_f32_16x16x32_bf16 v[96:99], v[112:115], v[108:111], v[96:99]
	ds_read2_b64 v[112:115], v148 offset0:144 offset1:148
	v_pk_mul_f32 v[102:103], v[66:67], v[104:105] op_sel_hi:[1,0]
	v_pk_mul_f32 v[100:101], v[64:65], v[104:105] op_sel_hi:[1,0]
	v_add_u32_e32 v116, 0x3000, v116
	v_fmac_f32_e32 v146, v133, v104
	s_waitcnt lgkmcnt(0)
	v_mfma_f32_16x16x32_bf16 v[100:103], v[112:115], v[108:111], v[100:103]
	ds_read2_b64 v[112:115], v116 offset0:160 offset1:164
	v_pk_mul_f32 v[106:107], v[62:63], v[104:105] op_sel_hi:[1,0]
	v_pk_mul_f32 v[104:105], v[60:61], v[104:105] op_sel_hi:[1,0]
	s_waitcnt lgkmcnt(0)
	s_nop 0
	v_mfma_f32_16x16x32_bf16 v[108:111], v[112:115], v[108:111], v[104:107]
	s_nop 2
	ds_read2_b64 v[104:107], v117 offset0:136 offset1:140
	v_cvt_pk_bf16_f32 v112, v118, v119
	v_cvt_pk_bf16_f32 v113, v120, v121
	v_cvt_pk_bf16_f32 v114, v122, v123
	v_cvt_pk_bf16_f32 v115, v143, v145
	v_mov_b32_e32 v143, v141
	s_waitcnt lgkmcnt(0)
	v_mfma_f32_16x16x32_bf16 v[92:95], v[104:107], v[112:115], v[92:95]
	ds_read2_b64 v[104:107], v147 offset0:136 offset1:140
	s_waitcnt lgkmcnt(0)
	v_mfma_f32_16x16x32_bf16 v[96:99], v[104:107], v[112:115], v[96:99]
	ds_read2_b64 v[104:107], v148 offset0:152 offset1:156
	s_waitcnt lgkmcnt(0)
	v_mfma_f32_16x16x32_bf16 v[104:107], v[104:107], v[112:115], v[100:103]
	s_nop 2
	ds_read2_b64 v[100:103], v116 offset0:168 offset1:172
	s_waitcnt lgkmcnt(0)
	v_mfma_f32_16x16x32_bf16 v[116:119], v[100:103], v[112:115], v[108:111]
	s_branch .LBB0_662

; template <bool BOUNDARY, bool Q0, bool Q1>
; __device__ __forceinline__ void attn_tile(const bf16* Ks, const bf16* Vt, const bf16x8 (&Qf)[2][2], const uint32_t (&vm)[2],
;                                           float (&m)[2], float (&l)[2], f32x4 (&O)[4][2], int fr, int fq) {
;     ...
; #pragma unroll
;   for (int kt = 0; kt < 4; ++kt) {
;     S[kt][0] = f32x4{0.f, 0.f, 0.f, 0.f};
;     S[kt][1] = f32x4{0.f, 0.f, 0.f, 0.f};
; #pragma unroll
;     for (int ks = 0; ks < 2; ++ks) {
;       const bf16x8 kf = *(const bf16x8*)(Ks + (16 * kt + fr) * KS_LD + 32 * ks + 8 * fq);
;       if (Q0) S[kt][0] = __builtin_amdgcn_mfma_f32_16x16x32_bf16(kf, Qf[0][ks], S[kt][0], 0, 0, 0);
;       if (Q1) S[kt][1] = __builtin_amdgcn_mfma_f32_16x16x32_bf16(kf, Qf[1][ks], S[kt][1], 0, 0, 0);
;     }
;   }
; #pragma unroll
;   for (int qt = 0; qt < 2; ++qt) {
;     if ((qt == 0 && !Q0) || (qt == 1 && !Q1)) continue;
;     float mx, mxu;
;     if (BOUNDARY) {
;       mx = m[qt];
; #pragma unroll
;       for (int kt = 0; kt < 4; ++kt)
; #pragma unroll
;         for (int j = 0; j < 4; ++j) {
;           const float s2 = S[kt][qt][j];
;           if ((vm[qt] >> (kt * 4 + j)) & 1u) mx = fmaxf(mx, s2);
;         }
;       mx = fmaxf(mx, __shfl_xor(mx, 16));
;       mx = fmaxf(mx, __shfl_xor(mx, 32));
;       mxu = mx;
;     } else {
;       float rm = -3.0e38f;
; #pragma unroll
;       for (int kt = 0; kt < 4; ++kt)
; #pragma unroll
;         for (int j = 0; j < 4; ++j) {
;           rm = fmaxf(rm, S[kt][qt][j]);
;         }
;       rm = fmaxf(rm, __shfl_xor(rm, 16));
;       rm = fmaxf(rm, __shfl_xor(rm, 32));
;       const bool rv = vm[qt] != 0u;
;       mx = rv ? fmaxf(m[qt], rm) : m[qt];
;       mxu = rv ? mx : 3.0e38f;
;     }
;     const float alpha = __builtin_amdgcn_exp2f(m[qt] - mx);
;     m[qt] = mx;
;     float ls = 0.f;
; #pragma unroll
;     for (int kt = 0; kt < 4; ++kt)
; #pragma unroll
;       for (int j = 0; j < 4; ++j) {
;         float pv;
;         if (BOUNDARY) pv = ((vm[qt] >> (kt * 4 + j)) & 1u) ? __builtin_amdgcn_exp2f(S[kt][qt][j] - mxu) : 0.f;
;         else pv = __builtin_amdgcn_exp2f(S[kt][qt][j] - mxu);
;         S[kt][qt][j] = pv;
;         ls += pv;
;       }
;     l[qt] = l[qt] * alpha + ls;
; #pragma unroll
;     for (int dt = 0; dt < 4; ++dt) {
;       O[dt][qt][0] *= alpha; O[dt][qt][1] *= alpha; O[dt][qt][2] *= alpha; O[dt][qt][3] *= alpha;
;     }
;   }
.LBB0_665:
	s_andn2_b64 vcc, exec, s[8:9]
	s_cbranch_vccnz .LBB0_675
	v_add_u32_e32 v104, v138, v152
	v_add_u32_e32 v147, v104, v230
	v_add_u32_e32 v143, v104, v163
	ds_read_b128 v[100:103], v147
	ds_read_b128 v[144:147], v147 offset:64
	ds_read_b128 v[96:99], v143
	ds_read_b128 v[108:111], v143 offset:64
	ds_read_b128 v[92:95], v143 offset:2304
	ds_read_b128 v[104:107], v143 offset:4608
	v_cmp_ne_u32_e32 vcc, 0, v142
	s_waitcnt lgkmcnt(5)
	v_mfma_f32_16x16x32_bf16 v[120:123], v[100:103], v[0:3], 0
	v_mfma_f32_16x16x32_bf16 v[100:103], v[100:103], v[8:11], 0
	s_waitcnt lgkmcnt(4)
	v_mfma_f32_16x16x32_bf16 v[120:123], v[144:147], v[4:7], v[120:123]
	v_mfma_f32_16x16x32_bf16 v[100:103], v[144:147], v[12:15], v[100:103]
	ds_read_b128 v[144:147], v143 offset:2368
	s_waitcnt lgkmcnt(3)
	v_mfma_f32_16x16x32_bf16 v[116:119], v[96:99], v[0:3], 0
	v_mfma_f32_16x16x32_bf16 v[96:99], v[96:99], v[8:11], 0
	v_mfma_f32_16x16x32_bf16 v[116:119], v[108:111], v[4:7], v[116:119]
	v_mfma_f32_16x16x32_bf16 v[96:99], v[108:111], v[12:15], v[96:99]
	s_waitcnt lgkmcnt(0)
	v_mfma_f32_16x16x32_bf16 v[112:115], v[92:95], v[0:3], 0
	v_mfma_f32_16x16x32_bf16 v[92:95], v[92:95], v[8:11], 0
	v_mfma_f32_16x16x32_bf16 v[112:115], v[144:147], v[4:7], v[112:115]
	v_mfma_f32_16x16x32_bf16 v[92:95], v[144:147], v[12:15], v[92:95]
	ds_read_b128 v[144:147], v143 offset:4672
	v_mfma_f32_16x16x32_bf16 v[108:111], v[104:107], v[0:3], 0
	v_mfma_f32_16x16x32_bf16 v[104:107], v[104:107], v[8:11], 0
	s_waitcnt lgkmcnt(0)
	v_mfma_f32_16x16x32_bf16 v[108:111], v[144:147], v[4:7], v[108:111]
	v_mfma_f32_16x16x32_bf16 v[104:107], v[144:147], v[12:15], v[104:107]
	v_max3_f32 v143, v120, s49, v121
	v_max3_f32 v143, v143, v122, v123
	v_max3_f32 v143, v143, v116, v117
	v_max3_f32 v143, v143, v118, v119
	v_max3_f32 v143, v143, v112, v113
	v_max3_f32 v143, v143, v114, v115
	s_nop 1
	v_max3_f32 v144, v100, s49, v101
	v_max3_f32 v144, v144, v102, v103
	v_max3_f32 v144, v144, v96, v97
	v_max3_f32 v144, v144, v98, v99
	v_max3_f32 v144, v144, v92, v93
	v_max3_f32 v144, v144, v94, v95
	v_max3_f32 v143, v143, v108, v109
	v_max3_f32 v143, v143, v110, v111
	v_max3_f32 v144, v144, v104, v105
	v_max3_f32 v144, v144, v106, v107
	s_nop 1
	v_permlane32_swap_b32_e32 v143, v144
	v_max_f32_e32 v145, v143, v144
	v_mov_b32_e32 v146, v145
	s_nop 1
	v_permlane16_swap_b32_e32 v145, v146
	v_max_f32_e32 v145, v145, v146
	v_mov_b32_e32 v146, v145
	s_nop 1
	v_permlane32_swap_b32_e32 v145, v146
	v_mov_b32_e32 v142, 0x7f61b1e6
	v_max_f32_e32 v145, v141, v145
	v_cndmask_b32_e32 v143, v141, v145, vcc
	v_cndmask_b32_e32 v142, v142, v143, vcc
	v_cmp_ne_u32_e32 vcc, 0, v140
	v_mov_b32_e32 v140, 0x7f61b1e6
	v_max_f32_e32 v146, v139, v146
	v_cndmask_b32_e32 v144, v139, v146, vcc
	s_nop 0
	v_cndmask_b32_e32 v140, v140, v144, vcc
	v_pk_add_f32 v[120:121], v[120:121], v[142:143] op_sel_hi:[1,0] neg_lo:[0,1] neg_hi:[0,1]
	v_pk_add_f32 v[122:123], v[122:123], v[142:143] op_sel_hi:[1,0] neg_lo:[0,1] neg_hi:[0,1]
	v_pk_add_f32 v[116:117], v[116:117], v[142:143] op_sel_hi:[1,0] neg_lo:[0,1] neg_hi:[0,1]
	v_pk_add_f32 v[118:119], v[118:119], v[142:143] op_sel_hi:[1,0] neg_lo:[0,1] neg_hi:[0,1]
	v_pk_add_f32 v[112:113], v[112:113], v[142:143] op_sel_hi:[1,0] neg_lo:[0,1] neg_hi:[0,1]
	v_pk_add_f32 v[114:115], v[114:115], v[142:143] op_sel_hi:[1,0] neg_lo:[0,1] neg_hi:[0,1]
	v_pk_add_f32 v[108:109], v[108:109], v[142:143] op_sel_hi:[1,0] neg_lo:[0,1] neg_hi:[0,1]
	v_pk_add_f32 v[110:111], v[110:111], v[142:143] op_sel_hi:[1,0] neg_lo:[0,1] neg_hi:[0,1]
	v_sub_f32_e32 v141, v141, v143
	v_sub_f32_e32 v100, v100, v140
	v_exp_f32_e32 v120, v120
	v_exp_f32_e32 v121, v121
	v_exp_f32_e32 v122, v122
	v_exp_f32_e32 v123, v123
	v_exp_f32_e32 v116, v116
	v_exp_f32_e32 v117, v117
	v_exp_f32_e32 v118, v118
	v_exp_f32_e32 v119, v119
	v_exp_f32_e32 v112, v112
	v_exp_f32_e32 v113, v113
	v_exp_f32_e32 v114, v114
	v_exp_f32_e32 v115, v115
	v_exp_f32_e32 v147, v108
	v_exp_f32_e32 v109, v109
	v_exp_f32_e32 v110, v110
	v_exp_f32_e32 v111, v111
	v_add_f32_e32 v145, 0, v120
	v_add_f32_e32 v145, v121, v145
	v_add_f32_e32 v145, v122, v145
	v_add_f32_e32 v145, v123, v145
	v_add_f32_e32 v145, v116, v145
	v_add_f32_e32 v145, v117, v145
	v_add_f32_e32 v145, v118, v145
	v_add_f32_e32 v145, v119, v145
	v_add_f32_e32 v145, v112, v145
	v_add_f32_e32 v145, v113, v145
	v_add_f32_e32 v145, v114, v145
	v_add_f32_e32 v145, v115, v145
	v_add_f32_e32 v108, v147, v145
	v_add_f32_e32 v108, v109, v108
	v_add_f32_e32 v108, v110, v108
	v_add_f32_e32 v145, v111, v108
	v_exp_f32_e32 v108, v141
	v_exp_f32_e32 v100, v100
	v_sub_f32_e32 v101, v101, v140
	v_exp_f32_e32 v101, v101
	v_sub_f32_e32 v102, v102, v140
	v_exp_f32_e32 v102, v102
	v_sub_f32_e32 v103, v103, v140
	v_exp_f32_e32 v103, v103
	v_sub_f32_e32 v96, v96, v140
	v_fmac_f32_e32 v145, v132, v108
	v_pk_mul_f32 v[90:91], v[90:91], v[108:109] op_sel_hi:[1,0]
	v_pk_mul_f32 v[88:89], v[88:89], v[108:109] op_sel_hi:[1,0]
	v_pk_mul_f32 v[86:87], v[86:87], v[108:109] op_sel_hi:[1,0]
	v_pk_mul_f32 v[84:85], v[84:85], v[108:109] op_sel_hi:[1,0]
	v_pk_mul_f32 v[82:83], v[82:83], v[108:109] op_sel_hi:[1,0]
	v_pk_mul_f32 v[80:81], v[80:81], v[108:109] op_sel_hi:[1,0]
	v_pk_mul_f32 v[78:79], v[78:79], v[108:109] op_sel_hi:[1,0]
	v_pk_mul_f32 v[76:77], v[76:77], v[108:109] op_sel_hi:[1,0]
	v_sub_f32_e32 v108, v139, v144
	v_add_f32_e32 v132, 0, v100
	v_exp_f32_e32 v139, v96
	v_add_f32_e32 v132, v101, v132
	v_add_f32_e32 v132, v102, v132
	v_add_f32_e32 v132, v103, v132
	v_sub_f32_e32 v97, v97, v140
	v_add_f32_e32 v96, v139, v132
	v_exp_f32_e32 v132, v97
	v_sub_f32_e32 v97, v98, v140
	v_exp_f32_e32 v141, v97
	v_sub_f32_e32 v97, v99, v140
	v_exp_f32_e32 v99, v97
	v_sub_f32_e32 v92, v92, v140
	v_exp_f32_e32 v142, v92
	v_sub_f32_e32 v93, v93, v140
	v_add_f32_e32 v96, v132, v96
	v_exp_f32_e32 v148, v93
	v_sub_f32_e32 v93, v94, v140
	v_add_f32_e32 v96, v141, v96
	v_exp_f32_e32 v149, v93
	v_sub_f32_e32 v93, v95, v140
	v_add_f32_e32 v96, v99, v96
	v_exp_f32_e32 v150, v93
	v_sub_f32_e32 v93, v104, v140
	v_add_f32_e32 v92, v142, v96
	v_exp_f32_e32 v104, v93
	v_sub_f32_e32 v93, v105, v140
	v_add_f32_e32 v92, v148, v92
	v_exp_f32_e32 v105, v93
	v_sub_f32_e32 v93, v106, v140
	v_add_f32_e32 v92, v149, v92
	v_exp_f32_e32 v106, v93
	v_sub_f32_e32 v93, v107, v140
	v_add_f32_e32 v92, v150, v92
	v_exp_f32_e32 v107, v93
	v_add_f32_e32 v92, v104, v92
	v_add_f32_e32 v92, v105, v92
	v_add_f32_e32 v92, v106, v92
	s_waitcnt lgkmcnt(0)
; template <bool BOUNDARY, bool Q0, bool Q1>
; __device__ __forceinline__ void attn_tile(const bf16* Ks, const bf16* Vt, const bf16x8 (&Qf)[2][2], const uint32_t (&vm)[2],
;                                           float (&m)[2], float (&l)[2], f32x4 (&O)[4][2], int fr, int fq) {
;     ...
;     l[qt] = l[qt] * alpha + ls;
; #pragma unroll
;     for (int dt = 0; dt < 4; ++dt) {
;       O[dt][qt][0] *= alpha; O[dt][qt][1] *= alpha; O[dt][qt][2] *= alpha; O[dt][qt][3] *= alpha;
;     }
;   }
; #pragma unroll
;   for (int kp = 0; kp < 2; ++kp) {
;     bf16x8 Pf[2];
; #pragma unroll
;     for (int qt = 0; qt < 2; ++qt) {
;       const u32x4 pk = {pack2(S[2 * kp][qt][0], S[2 * kp][qt][1]), pack2(S[2 * kp][qt][2], S[2 * kp][qt][3]),
;                         pack2(S[2 * kp + 1][qt][0], S[2 * kp + 1][qt][1]), pack2(S[2 * kp + 1][qt][2], S[2 * kp + 1][qt][3])};
;       Pf[qt] = __builtin_bit_cast(bf16x8, pk);
;     }
; #pragma unroll
;     for (int dt = 0; dt < 4; ++dt) {
;       const bf16x4 v0 = *(const bf16x4*)(Vt + (16 * dt + fr) * VT_LD + 32 * kp + 4 * fq);
;       const bf16x4 v1 = *(const bf16x4*)(Vt + (16 * dt + fr) * VT_LD + 32 * kp + 16 + 4 * fq);
;       bf16x8 vf;
;       vf[0] = v0[0]; vf[1] = v0[1]; vf[2] = v0[2]; vf[3] = v0[3];
;       vf[4] = v1[0]; vf[5] = v1[1]; vf[6] = v1[2]; vf[7] = v1[3];
;       if (Q0) O[dt][0] = __builtin_amdgcn_mfma_f32_16x16x32_bf16(vf, Pf[0], O[dt][0], 0, 0, 0);
;       if (Q1) O[dt][1] = __builtin_amdgcn_mfma_f32_16x16x32_bf16(vf, Pf[1], O[dt][1], 0, 0, 0);
;     }
;   }
	v_add_f32_e32 v146, v107, v92
	v_exp_f32_e32 v92, v108
	v_lshlrev_b32_e32 v108, 1, v223
	v_cvt_pk_bf16_f32 v96, v100, v101
	v_add3_u32 v100, v138, v231, v108
	v_fmac_f32_e32 v146, v133, v92
	v_pk_mul_f32 v[74:75], v[74:75], v[92:93] op_sel_hi:[1,0]
	v_pk_mul_f32 v[72:73], v[72:73], v[92:93] op_sel_hi:[1,0]
	v_pk_mul_f32 v[70:71], v[70:71], v[92:93] op_sel_hi:[1,0]
	v_pk_mul_f32 v[68:69], v[68:69], v[92:93] op_sel_hi:[1,0]
	v_pk_mul_f32 v[66:67], v[66:67], v[92:93] op_sel_hi:[1,0]
	v_pk_mul_f32 v[64:65], v[64:65], v[92:93] op_sel_hi:[1,0]
	v_pk_mul_f32 v[62:63], v[62:63], v[92:93] op_sel_hi:[1,0]
	v_pk_mul_f32 v[60:61], v[60:61], v[92:93] op_sel_hi:[1,0]
	v_cvt_pk_bf16_f32 v92, v120, v121
	v_add_u32_e32 v120, 0x2000, v100
	v_cvt_pk_bf16_f32 v97, v102, v103
	v_cvt_pk_bf16_f32 v93, v122, v123
	ds_read2_b64 v[100:103], v120 offset0:128 offset1:132
	v_cvt_pk_bf16_f32 v94, v116, v117
	v_cvt_pk_bf16_f32 v95, v118, v119
	v_cvt_pk_bf16_f32 v98, v139, v132
	v_cvt_pk_bf16_f32 v99, v141, v99
	v_lshlrev_b32_e32 v132, 1, v233
	v_add3_u32 v108, v138, v132, v108
	v_add_u32_e32 v121, 0x2000, v108
	v_add_u32_e32 v122, 0x2800, v108
	v_add_u32_e32 v123, 0x3000, v108
	v_cvt_pk_bf16_f32 v116, v112, v113
	v_cvt_pk_bf16_f32 v117, v114, v115
	ds_read2_b64 v[112:115], v122 offset0:144 offset1:148
	v_cvt_pk_bf16_f32 v118, v147, v109
	v_cvt_pk_bf16_f32 v119, v110, v111
	ds_read2_b64 v[108:111], v123 offset0:160 offset1:164
	v_cvt_pk_bf16_f32 v138, v142, v148
	v_cvt_pk_bf16_f32 v139, v149, v150
	v_cvt_pk_bf16_f32 v140, v104, v105
	v_cvt_pk_bf16_f32 v141, v106, v107
	ds_read2_b64 v[104:107], v121 offset0:128 offset1:132
	s_waitcnt lgkmcnt(3)
	v_mfma_f32_16x16x32_bf16 v[88:91], v[100:103], v[92:95], v[88:91]
	v_mfma_f32_16x16x32_bf16 v[72:75], v[100:103], v[96:99], v[72:75]
	ds_read2_b64 v[100:103], v120 offset0:136 offset1:140
	s_waitcnt lgkmcnt(3)
	v_mfma_f32_16x16x32_bf16 v[80:83], v[112:115], v[92:95], v[80:83]
	v_mfma_f32_16x16x32_bf16 v[64:67], v[112:115], v[96:99], v[64:67]
	ds_read2_b64 v[112:115], v122 offset0:152 offset1:156
	s_waitcnt lgkmcnt(3)
	v_mfma_f32_16x16x32_bf16 v[76:79], v[108:111], v[92:95], v[76:79]
	v_mfma_f32_16x16x32_bf16 v[60:63], v[108:111], v[96:99], v[60:63]
	ds_read2_b64 v[108:111], v121 offset0:136 offset1:140
	s_waitcnt lgkmcnt(3)
	v_mfma_f32_16x16x32_bf16 v[84:87], v[104:107], v[92:95], v[84:87]
	v_mfma_f32_16x16x32_bf16 v[68:71], v[104:107], v[96:99], v[68:71]
	ds_read2_b64 v[148:151], v123 offset0:168 offset1:172
	s_waitcnt lgkmcnt(3)
	v_mfma_f32_16x16x32_bf16 v[92:95], v[100:103], v[138:141], v[72:75]
	v_mfma_f32_16x16x32_bf16 v[100:103], v[100:103], v[116:119], v[88:91]
	s_waitcnt lgkmcnt(2)
	v_mfma_f32_16x16x32_bf16 v[104:107], v[112:115], v[138:141], v[64:67]
	v_mfma_f32_16x16x32_bf16 v[112:115], v[112:115], v[116:119], v[80:83]
	s_waitcnt lgkmcnt(1)
	v_mfma_f32_16x16x32_bf16 v[96:99], v[108:111], v[138:141], v[68:71]
	v_mfma_f32_16x16x32_bf16 v[108:111], v[108:111], v[116:119], v[84:87]
	s_waitcnt lgkmcnt(0)
	v_mfma_f32_16x16x32_bf16 v[120:123], v[148:151], v[116:119], v[76:79]
	v_mfma_f32_16x16x32_bf16 v[116:119], v[148:151], v[138:141], v[60:63]
